# v90 + out-proj residual-stream (XB) stores write-through (sc1), re-tested with a paired measure
# baseline (speedup 1.0000x reference)
; #define LAS __attribute__((address_space(3)))
; __device__ __forceinline__ int crow(int r, int hi) { return (r & 3) + 8 * (r >> 2) + 4 * hi; }
; __device__ __forceinline__ void g2_sample_tile(const bf16_t* __restrict__ Y, const bf16_t* __restrict__ Wt, const float* xs  , const bf16_t* xbs  , float* outs  , bf16_t* outbs  , const float* __restrict__ gate, ...
;     const int row0 = (tile >> 4) * 64, col0 = (tile & 15) * 64, m = lane & 31, kq = lane >> 5;
;     f32x16 acc[2][2];
; #pragma unroll
;     for (int i2 = 0; i2 < 2; ++i2)
; #pragma unroll
;         for (int j2 = 0; j2 < 2; ++j2)
; #pragma unroll
;             for (int i = 0; i < 16; ++i) acc[i2][j2][i] = 0.f;
;     const bf16_t* ap = Y + (size_t)(MP + row0 + m) * D + wave * 128 + kq * 8;
;     const bf16_t* bp = Wt + (size_t)(col0 + m) * D + wave * 128 + kq * 8;
; #pragma unroll
;     for (int ks = 0; ks < 8; ++ks) {
;         const bf16x8 a0 = *(const bf16x8*)(ap + ks * 16), a1 = *(const bf16x8*)(ap + 32 * D + ks * 16), b0 = *(const bf16x8*)(bp + ks * 16), b1 = *(const bf16x8*)(bp + 32 * D + ks * 16);
;         acc[0][0] = __builtin_amdgcn_mfma_f32_32x32x16_bf16(a0, b0, acc[0][0], 0, 0, 0); acc[0][1] = __builtin_amdgcn_mfma_f32_32x32x16_bf16(a0, b1, acc[0][1], 0, 0, 0);
;         acc[1][0] = __builtin_amdgcn_mfma_f32_32x32x16_bf16(a1, b0, acc[1][0], 0, 0, 0); acc[1][1] = __builtin_amdgcn_mfma_f32_32x32x16_bf16(a1, b1, acc[1][1], 0, 0, 0);
;     }
;     LAS float* slab = (LAS float*)lds + wave * 4096;
; #pragma unroll
;     for (int i2 = 0; i2 < 2; ++i2)
; #pragma unroll
;         for (int j2 = 0; j2 < 2; ++j2)
; #pragma unroll
;             for (int i = 0; i < 16; ++i) slab[(32 * i2 + crow(i, kq)) * 64 + 32 * j2 + m] = acc[i2][j2][i];
;     __syncthreads();
.LBB0_594:
	s_and_b32 s21, s23, 0xffffffc0
	v_add_u32_e32 v0, s21, v78
	v_ashrrev_i32_e32 v1, 31, v0
	s_and_b32 s20, s22, 0x3c0
	v_lshlrev_b64 v[0:1], 11, v[0:1]
	v_lshl_add_u64 v[72:73], v[64:65], 0, v[0:1]
	v_or_b32_e32 v0, s20, v69
	v_lshlrev_b32_e32 v172, 11, v0
	global_load_dwordx4 v[0:3], v[72:73], off
	v_add_co_u32_e32 v74, vcc, 0x10000, v72
	v_lshl_add_u64 v[70:71], v[66:67], 0, v[172:173]
	s_nop 0
	v_addc_co_u32_e32 v75, vcc, 0, v73, vcc
	v_add_co_u32_e32 v76, vcc, 0x10000, v70
	global_load_dwordx4 v[16:19], v[74:75], off
	global_load_dwordx4 v[4:7], v[70:71], off
	v_addc_co_u32_e32 v77, vcc, 0, v71, vcc
	global_load_dwordx4 v[20:23], v[76:77], off
	global_load_dwordx4 v[90:93], v[72:73], off offset:32
	global_load_dwordx4 v[94:97], v[74:75], off offset:32
	global_load_dwordx4 v[98:101], v[70:71], off offset:32
	global_load_dwordx4 v[102:105], v[76:77], off offset:32
	global_load_dwordx4 v[106:109], v[72:73], off offset:64
	global_load_dwordx4 v[110:113], v[74:75], off offset:64
	global_load_dwordx4 v[114:117], v[70:71], off offset:64
	global_load_dwordx4 v[118:121], v[76:77], off offset:64
	global_load_dwordx4 v[122:125], v[72:73], off offset:96
	global_load_dwordx4 v[126:129], v[74:75], off offset:96
	global_load_dwordx4 v[132:135], v[70:71], off offset:96
	global_load_dwordx4 v[136:139], v[76:77], off offset:96
	global_load_dwordx4 v[140:143], v[72:73], off offset:128
	global_load_dwordx4 v[144:147], v[74:75], off offset:128
	global_load_dwordx4 v[148:151], v[70:71], off offset:128
	global_load_dwordx4 v[152:155], v[76:77], off offset:128
	global_load_dwordx4 v[156:159], v[72:73], off offset:160
	global_load_dwordx4 v[160:163], v[74:75], off offset:160
	global_load_dwordx4 v[164:167], v[70:71], off offset:160
	global_load_dwordx4 v[168:171], v[76:77], off offset:160
	global_load_dwordx4 v[182:185], v[72:73], off offset:192
	global_load_dwordx4 v[186:189], v[74:75], off offset:192
	global_load_dwordx4 v[190:193], v[70:71], off offset:192
	global_load_dwordx4 v[194:197], v[76:77], off offset:192
	global_load_dwordx4 v[198:201], v[72:73], off offset:224
	global_load_dwordx4 v[202:205], v[74:75], off offset:224
	global_load_dwordx4 v[236:239], v[70:71], off offset:224
	global_load_dwordx4 v[240:243], v[76:77], off offset:224
	s_lshl_b32 s86, s20, 2
	v_lshlrev_b32_e32 v172, 2, v68
	s_waitcnt vmcnt(29)
	v_mfma_f32_32x32x16_bf16 v[32:47], v[0:3], v[4:7], 0
	s_waitcnt vmcnt(28)
	v_mfma_f32_32x32x16_bf16 v[48:63], v[0:3], v[20:23], 0
	v_mfma_f32_32x32x16_bf16 v[0:15], v[16:19], v[4:7], 0
	v_mfma_f32_32x32x16_bf16 v[16:31], v[16:19], v[20:23], 0
	s_waitcnt vmcnt(24)
	v_mfma_f32_32x32x16_bf16 v[32:47], v[90:93], v[98:101], v[32:47]
	v_mfma_f32_32x32x16_bf16 v[48:63], v[90:93], v[102:105], v[48:63]
	v_mfma_f32_32x32x16_bf16 v[0:15], v[94:97], v[98:101], v[0:15]
	v_mfma_f32_32x32x16_bf16 v[16:31], v[94:97], v[102:105], v[16:31]
	s_waitcnt vmcnt(20)
	v_mfma_f32_32x32x16_bf16 v[32:47], v[106:109], v[114:117], v[32:47]
	v_mfma_f32_32x32x16_bf16 v[48:63], v[106:109], v[118:121], v[48:63]
	v_mfma_f32_32x32x16_bf16 v[0:15], v[110:113], v[114:117], v[0:15]
	v_mfma_f32_32x32x16_bf16 v[16:31], v[110:113], v[118:121], v[16:31]
	s_waitcnt vmcnt(16)
	v_mfma_f32_32x32x16_bf16 v[32:47], v[122:125], v[132:135], v[32:47]
	v_mfma_f32_32x32x16_bf16 v[48:63], v[122:125], v[136:139], v[48:63]
	v_mfma_f32_32x32x16_bf16 v[0:15], v[126:129], v[132:135], v[0:15]
	v_mfma_f32_32x32x16_bf16 v[16:31], v[126:129], v[136:139], v[16:31]
	s_waitcnt vmcnt(12)
	v_mfma_f32_32x32x16_bf16 v[32:47], v[140:143], v[148:151], v[32:47]
	v_mfma_f32_32x32x16_bf16 v[48:63], v[140:143], v[152:155], v[48:63]
	v_mfma_f32_32x32x16_bf16 v[0:15], v[144:147], v[148:151], v[0:15]
	v_mfma_f32_32x32x16_bf16 v[16:31], v[144:147], v[152:155], v[16:31]
	s_waitcnt vmcnt(8)
	v_mfma_f32_32x32x16_bf16 v[32:47], v[156:159], v[164:167], v[32:47]
	v_mfma_f32_32x32x16_bf16 v[48:63], v[156:159], v[168:171], v[48:63]
	v_mfma_f32_32x32x16_bf16 v[0:15], v[160:163], v[164:167], v[0:15]
	v_mfma_f32_32x32x16_bf16 v[16:31], v[160:163], v[168:171], v[16:31]
	s_waitcnt vmcnt(4)
	v_mfma_f32_32x32x16_bf16 v[32:47], v[182:185], v[190:193], v[32:47]
	v_mfma_f32_32x32x16_bf16 v[48:63], v[182:185], v[194:197], v[48:63]
	v_mfma_f32_32x32x16_bf16 v[0:15], v[186:189], v[190:193], v[0:15]
	v_mfma_f32_32x32x16_bf16 v[16:31], v[186:189], v[194:197], v[16:31]
	s_waitcnt vmcnt(0)
	v_mfma_f32_32x32x16_bf16 v[32:47], v[198:201], v[236:239], v[32:47]
	v_mfma_f32_32x32x16_bf16 v[48:63], v[198:201], v[240:243], v[48:63]
	s_nop 11
	ds_write2_b32 v79, v32, v48 offset1:32
	ds_write2_b32 v79, v33, v49 offset0:64 offset1:96
	ds_write2_b32 v79, v34, v50 offset0:128 offset1:160
	ds_write2_b32 v79, v35, v51 offset0:192 offset1:224
	v_mfma_f32_32x32x16_bf16 v[0:15], v[202:205], v[236:239], v[0:15]
	v_add_u32_e32 v32, 0x800, v79
	ds_write2_b32 v32, v36, v52 offset1:32
	ds_write2_b32 v32, v37, v53 offset0:64 offset1:96
	ds_write2_b32 v32, v38, v54 offset0:128 offset1:160
	ds_write2_b32 v32, v39, v55 offset0:192 offset1:224
	v_add_u32_e32 v32, 0x1000, v79
	ds_write2_b32 v32, v40, v56 offset1:32
	ds_write2_b32 v32, v41, v57 offset0:64 offset1:96
	ds_write2_b32 v32, v42, v58 offset0:128 offset1:160
	ds_write2_b32 v32, v43, v59 offset0:192 offset1:224
	v_add_u32_e32 v32, 0x1800, v79
	ds_write2_b32 v32, v44, v60 offset1:32
	ds_write2_b32 v32, v45, v61 offset0:64 offset1:96
	ds_write2_b32 v32, v46, v62 offset0:128 offset1:160
	ds_write2_b32 v32, v47, v63 offset0:192 offset1:224
	v_add_u32_e32 v32, 0x2000, v79
	v_mfma_f32_32x32x16_bf16 v[16:31], v[202:205], v[240:243], v[16:31]
	s_nop 11
	ds_write2_b32 v32, v0, v16 offset1:32
	ds_write2_b32 v32, v1, v17 offset0:64 offset1:96
	ds_write2_b32 v32, v2, v18 offset0:128 offset1:160
	ds_write2_b32 v32, v3, v19 offset0:192 offset1:224
	v_add_u32_e32 v0, 0x2800, v79
	ds_write2_b32 v0, v4, v20 offset1:32
	ds_write2_b32 v0, v5, v21 offset0:64 offset1:96
	ds_write2_b32 v0, v6, v22 offset0:128 offset1:160
	ds_write2_b32 v0, v7, v23 offset0:192 offset1:224
	v_add_u32_e32 v0, 0x3000, v79
	ds_write2_b32 v0, v8, v24 offset1:32
	ds_write2_b32 v0, v9, v25 offset0:64 offset1:96
	ds_write2_b32 v0, v10, v26 offset0:128 offset1:160
	ds_write2_b32 v0, v11, v27 offset0:192 offset1:224
	v_add_u32_e32 v0, 0x3800, v79
	ds_write2_b32 v0, v12, v28 offset1:32
	ds_write2_b32 v0, v13, v29 offset0:64 offset1:96
	ds_write2_b32 v0, v14, v30 offset0:128 offset1:160
	ds_write2_b32 v0, v15, v31 offset0:192 offset1:224
	s_waitcnt lgkmcnt(0)
	s_barrier
; #define LAS __attribute__((address_space(3)))
; __device__ __forceinline__ void g2_sample_tile(const bf16_t* __restrict__ Y, const bf16_t* __restrict__ Wt, const float* xs  , const bf16_t* xbs  , float* outs  , bf16_t* outbs  , const float* __restrict__ gate, ...
;     ...
;     const int r = tid >> 3, c8 = (tid & 7) * 8;
;     f32x4 s0 = {0.f, 0.f, 0.f, 0.f}, s1 = {0.f, 0.f, 0.f, 0.f};
; #pragma unroll
;     for (int w = 0; w < 8; ++w) { const LAS float* sp = (const LAS float*)lds + w * 4096 + r * 64 + c8; s0 += *(const LAS f32x4*)sp; s1 += *(const LAS f32x4*)(sp + 4); }
;     const int srow = row0 + r, nidx = NPB + (srow >> 3);
;     const size_t ro = (size_t)srow * D + col0 + c8; const float* gp = gate + (size_t)nidx * 3072 + col0 + c8;
;     const f32x4 g0 = *(const f32x4*)gp, g1 = *(const f32x4*)(gp + 4);
;     f32x4 x0, x1;
;     if (xs) { x0 = *(const f32x4*)(xs + ro); x1 = *(const f32x4*)(xs + ro + 4); }
;     else { const u32x4 w = __builtin_nontemporal_load((const u32x4*)(xbs + ro));
;         x0 = (f32x4){__uint_as_float(w.x << 16), __uint_as_float(w.x & 0xffff0000u), __uint_as_float(w.y << 16), __uint_as_float(w.y & 0xffff0000u)};
;         x1 = (f32x4){__uint_as_float(w.z << 16), __uint_as_float(w.z & 0xffff0000u), __uint_as_float(w.w << 16), __uint_as_float(w.w & 0xffff0000u)}; }
;     const f32x4 v0 = x0 + g0 * s0, v1 = x1 + g1 * s1;
;     if (outbs) { u32x4 w; w.x = pk_bf16(v0[0], v0[1]); w.y = pk_bf16(v0[2], v0[3]); w.z = pk_bf16(v1[0], v1[1]); w.w = pk_bf16(v1[2], v1[3]); *(u32x4*)(outbs + ro) = w; }
;     else { *(f32x4*)(outs + ro) = v0; *(f32x4*)(outs + ro + 4) = v1; }
	v_add_u32_e32 v0, s21, v80
	v_ashrrev_i32_e32 v1, 3, v0
	v_add_u32_e32 v2, 4, v1
	v_ashrrev_i32_e32 v1, 31, v0
	v_lshlrev_b64 v[16:17], 10, v[0:1]
	v_or_b32_e32 v0, s20, v16
	v_or_b32_e32 v16, v0, v68
	v_mov_b64_e32 v[0:1], s[4:5]
	s_movk_i32 s21, 0x3000
	v_mad_i64_i32 v[0:1], s[26:27], v2, s21, v[0:1]
	v_lshl_add_u64 v[0:1], v[0:1], 0, s[86:87]
	v_lshl_add_u64 v[4:5], v[0:1], 0, v[172:173]
	v_lshl_add_u64 v[18:19], v[16:17], 1, s[10:11]
	global_load_dwordx4 v[106:109], v[4:5], off offset:16
	global_load_dwordx4 v[110:113], v[4:5], off
	global_load_dwordx4 v[114:117], v[18:19], off nt
	ds_read_b128 v[20:23], v81
	ds_read_b128 v[24:27], v81 offset:16
	ds_read_b128 v[28:31], v81 offset:16384
	ds_read_b128 v[32:35], v81 offset:16400
	ds_read_b128 v[36:39], v81 offset:32768
	ds_read_b128 v[40:43], v81 offset:32784
	ds_read_b128 v[44:47], v81 offset:49152
	ds_read_b128 v[48:51], v81 offset:49168
	ds_read_b128 v[52:55], v82
	ds_read_b128 v[56:59], v83
	ds_read_b128 v[60:63], v84
	ds_read_b128 v[90:93], v85
	ds_read_b128 v[94:97], v86
	ds_read_b128 v[98:101], v87
	ds_read_b128 v[102:105], v88
	ds_read_b128 v[118:121], v89
	v_readlane_b32 s26, v255, 8
	v_readlane_b32 s27, v255, 9
	s_mov_b64 s[20:21], -1
	s_waitcnt lgkmcnt(14)
	v_pk_add_f32 v[8:9], v[22:23], 0 op_sel_hi:[1,0]
	v_pk_add_f32 v[10:11], v[20:21], 0 op_sel_hi:[1,0]
	v_pk_add_f32 v[6:7], v[26:27], 0 op_sel_hi:[1,0]
	v_pk_add_f32 v[4:5], v[24:25], 0 op_sel_hi:[1,0]
	s_waitcnt lgkmcnt(12)
	v_pk_add_f32 v[8:9], v[8:9], v[30:31]
	v_pk_add_f32 v[10:11], v[10:11], v[28:29]
	v_pk_add_f32 v[6:7], v[6:7], v[34:35]
	v_pk_add_f32 v[4:5], v[4:5], v[32:33]
	s_waitcnt lgkmcnt(10)
	v_pk_add_f32 v[8:9], v[8:9], v[38:39]
	v_pk_add_f32 v[10:11], v[10:11], v[36:37]
	v_pk_add_f32 v[6:7], v[6:7], v[42:43]
	v_pk_add_f32 v[4:5], v[4:5], v[40:41]
	s_waitcnt lgkmcnt(8)
	v_pk_add_f32 v[8:9], v[8:9], v[46:47]
	v_pk_add_f32 v[10:11], v[10:11], v[44:45]
	v_pk_add_f32 v[6:7], v[6:7], v[50:51]
	v_pk_add_f32 v[4:5], v[4:5], v[48:49]
	s_waitcnt lgkmcnt(6)
	v_pk_add_f32 v[8:9], v[8:9], v[54:55]
	v_pk_add_f32 v[10:11], v[10:11], v[52:53]
	v_pk_add_f32 v[6:7], v[6:7], v[58:59]
	v_pk_add_f32 v[4:5], v[4:5], v[56:57]
	s_waitcnt lgkmcnt(4)
	v_pk_add_f32 v[8:9], v[8:9], v[62:63]
	v_pk_add_f32 v[10:11], v[10:11], v[60:61]
	v_pk_add_f32 v[6:7], v[6:7], v[92:93]
	v_pk_add_f32 v[4:5], v[4:5], v[90:91]
	s_waitcnt lgkmcnt(2)
	v_pk_add_f32 v[8:9], v[8:9], v[96:97]
	v_pk_add_f32 v[10:11], v[10:11], v[94:95]
	v_pk_add_f32 v[6:7], v[6:7], v[100:101]
	v_pk_add_f32 v[4:5], v[4:5], v[98:99]
	s_waitcnt lgkmcnt(0)
	v_pk_add_f32 v[12:13], v[8:9], v[104:105]
	v_pk_add_f32 v[14:15], v[10:11], v[102:103]
	v_pk_add_f32 v[10:11], v[4:5], v[118:119]
	v_pk_add_f32 v[8:9], v[6:7], v[120:121]
	s_and_b64 vcc, exec, s[26:27]
	s_waitcnt vmcnt(0)
	v_lshlrev_b32_e32 v22, 16, v114
	v_and_b32_e32 v23, 0xffff0000, v114
	v_lshlrev_b32_e32 v18, 16, v115
	v_and_b32_e32 v19, 0xffff0000, v115
	v_lshlrev_b32_e32 v24, 16, v116
	v_and_b32_e32 v25, 0xffff0000, v116
	v_lshlrev_b32_e32 v20, 16, v117
	v_and_b32_e32 v21, 0xffff0000, v117
	v_pk_fma_f32 v[4:5], v[14:15], v[110:111], v[22:23]
	v_pk_fma_f32 v[6:7], v[12:13], v[112:113], v[18:19]
	v_pk_fma_f32 v[0:1], v[10:11], v[106:107], v[24:25]
	v_pk_fma_f32 v[2:3], v[8:9], v[108:109], v[20:21]
	s_cbranch_vccz .LBB0_596
	v_readlane_b32 s20, v254, 24
	v_readlane_b32 s21, v254, 25
	s_nop 1
	v_lshl_add_u64 v[8:9], v[16:17], 2, s[20:21]
	global_store_dwordx4 v[8:9], v[4:7], off sc1
	global_store_dwordx4 v[8:9], v[0:3], off offset:16 sc1
	s_mov_b64 s[20:21], 0
.LBB0_596:
	s_andn2_b64 vcc, exec, s[20:21]
	s_cbranch_vccnz .LBB0_593
	v_readlane_b32 s20, v254, 26
	v_readlane_b32 s21, v254, 27
	v_cvt_pk_bf16_f32 v4, v4, v5
	v_cvt_pk_bf16_f32 v5, v6, v7
	v_cvt_pk_bf16_f32 v6, v0, v1
	v_cvt_pk_bf16_f32 v7, v2, v3
	v_lshl_add_u64 v[0:1], v[16:17], 1, s[20:21]
	global_store_dwordx4 v[0:1], v[4:7], off sc1
	s_branch .LBB0_593

; __device__ __forceinline__ unsigned cvt_pk_bf16(float lo, float hi) { unsigned r; asm volatile("v_cvt_pk_bf16_f32 %0, %1, %2" : "=v"(r) : "v"(lo), "v"(hi)); return r; }
;     __device__ __forceinline__ void operator()(const f32x4 (&acc)[2][2][4][2], const Unit& u, int wr, int wc, int fr, int fq) const {
;         const int col0 = u.pn * BM + wc * 32 + 8 * fq;
;         const float* gp = gate + (size_t)(u.pm >> 4) * 3072 + col0;
;         const bool l0 = first;
;         f32x4 gv[2][2];
; #pragma unroll
;         for (int bj = 0; bj < 2; ++bj)
; #pragma unroll
;             for (int nn = 0; nn < 2; ++nn) gv[bj][nn] = *(const f32x4*)(gp + bj * HALF + nn * 4);
; #pragma unroll
;         for (int ai = 0; ai < 2; ++ai) {
;             u32x4 xw[4][2];
; #pragma unroll
;             for (int mi = 0; mi < 4; ++mi) { const bf16_t* bp = xb + (size_t)(u.pm * BM + ai * HALF + wr * 64 + mi * 16 + fr) * 1024 + col0;
; #pragma unroll
;                 for (int bj = 0; bj < 2; ++bj) xw[mi][bj] = __builtin_nontemporal_load((const u32x4*)(bp + bj * HALF)); }
; #pragma unroll
;             for (int mi = 0; mi < 4; ++mi) { const size_t ro = (size_t)(u.pm * BM + ai * HALF + wr * 64 + mi * 16 + fr) * 1024 + col0;
; #pragma unroll
;                 for (int bj = 0; bj < 2; ++bj) { const u32x4 w = xw[mi][bj];
;                     const f32x4 x0 = (f32x4){__uint_as_float(w.x << 16), __uint_as_float(w.x & 0xffff0000u), __uint_as_float(w.y << 16), __uint_as_float(w.y & 0xffff0000u)};
;                     const f32x4 x1 = (f32x4){__uint_as_float(w.z << 16), __uint_as_float(w.z & 0xffff0000u), __uint_as_float(w.w << 16), __uint_as_float(w.w & 0xffff0000u)};
;                     const f32x4 v0 = x0 + gv[bj][0] * acc[ai][bj][mi][0], v1 = x1 + gv[bj][1] * acc[ai][bj][mi][1];
;                     if (l0) { u32x4 o; o.x = cvt_pk_bf16(v0[0], v0[1]); o.y = cvt_pk_bf16(v0[2], v0[3]); o.z = cvt_pk_bf16(v1[0], v1[1]); o.w = cvt_pk_bf16(v1[2], v1[3]);
;                               *(u32x4*)(outb + ro + bj * HALF) = o; }
;                     else { __builtin_nontemporal_store(v0, (f32x4*)(outf + ro + bj * HALF)); __builtin_nontemporal_store(v1, (f32x4*)(outf + ro + bj * HALF + 4)); }
.LBB0_616:
	s_ashr_i32 s25, s61, 4
	v_lshl_or_b32 v192, s62, 8, v229
	s_mul_hi_i32 s27, s25, 0x3000
	s_mulk_i32 s25, 0x3000
	v_lshl_add_u32 v196, s61, 8, v227
	s_add_u32 s34, s4, s25
	v_ashrrev_i32_e32 v193, 31, v192
	v_ashrrev_i32_e32 v197, 31, v196
	s_addc_u32 s35, s5, s27
	v_lshl_add_u64 v[194:195], v[192:193], 1, s[6:7]
	v_lshlrev_b64 v[144:145], 11, v[196:197]
	v_or_b32_e32 v202, 16, v196
	v_lshl_add_u64 v[72:73], v[192:193], 2, s[34:35]
	v_lshl_add_u64 v[144:145], v[194:195], 0, v[144:145]
	v_ashrrev_i32_e32 v203, 31, v202
	global_load_dwordx4 v[80:83], v[72:73], off offset:16
	global_load_dwordx4 v[84:87], v[72:73], off
	global_load_dwordx4 v[68:71], v[72:73], off offset:528
	s_nop 0
	global_load_dwordx4 v[72:75], v[72:73], off offset:512
	s_nop 0
	global_load_dwordx4 v[236:239], v[144:145], off nt
	global_load_dwordx4 v[168:171], v[144:145], off offset:256 nt
	v_lshlrev_b64 v[144:145], 11, v[202:203]
	v_or_b32_e32 v200, 32, v196
	v_lshl_add_u64 v[144:145], v[194:195], 0, v[144:145]
	v_ashrrev_i32_e32 v201, 31, v200
	global_load_dwordx4 v[164:167], v[144:145], off nt
	global_load_dwordx4 v[160:163], v[144:145], off offset:256 nt
	v_lshlrev_b64 v[144:145], 11, v[200:201]
	v_or_b32_e32 v198, 48, v196
	v_lshl_add_u64 v[144:145], v[194:195], 0, v[144:145]
	v_ashrrev_i32_e32 v199, 31, v198
	global_load_dwordx4 v[156:159], v[144:145], off nt
	global_load_dwordx4 v[152:155], v[144:145], off offset:256 nt
	v_lshlrev_b64 v[144:145], 11, v[198:199]
	v_lshl_add_u64 v[144:145], v[194:195], 0, v[144:145]
	global_load_dwordx4 v[148:151], v[144:145], off nt
	s_nop 0
	global_load_dwordx4 v[144:147], v[144:145], off offset:256 nt
	v_lshlrev_b64 v[204:205], 10, v[196:197]
	v_lshl_add_u64 v[206:207], v[204:205], 0, v[192:193]
	s_mov_b64 s[34:35], -1
	s_andn2_b64 vcc, exec, s[8:9]
	s_waitcnt vmcnt(0)
	v_lshlrev_b32_e32 v204, 16, v236
	v_and_b32_e32 v205, 0xffff0000, v236
	v_lshlrev_b32_e32 v210, 16, v237
	v_and_b32_e32 v211, 0xffff0000, v237
	v_lshlrev_b32_e32 v236, 16, v238
	v_and_b32_e32 v237, 0xffff0000, v238
	v_lshlrev_b32_e32 v238, 16, v239
	v_and_b32_e32 v239, 0xffff0000, v239
	v_pk_fma_f32 v[142:143], v[142:143], v[86:87], v[210:211]
	v_pk_fma_f32 v[140:141], v[140:141], v[84:85], v[204:205]
	v_pk_fma_f32 v[138:139], v[138:139], v[82:83], v[238:239]
	v_pk_fma_f32 v[136:137], v[136:137], v[80:81], v[236:237]
	v_lshl_add_u64 v[204:205], v[206:207], 1, s[58:59]
	s_cbranch_vccnz .LBB0_618
	s_mov_b64 s[34:35], 0
	v_cvt_pk_bf16_f32 v236, v140, v141
	v_cvt_pk_bf16_f32 v237, v142, v143
	v_cvt_pk_bf16_f32 v238, v136, v137
	v_cvt_pk_bf16_f32 v239, v138, v139
	global_store_dwordx4 v[204:205], v[236:239], off sc1

; __device__ __forceinline__ unsigned cvt_pk_bf16(float lo, float hi) { unsigned r; asm volatile("v_cvt_pk_bf16_f32 %0, %1, %2" : "=v"(r) : "v"(lo), "v"(hi)); return r; }
;     __device__ __forceinline__ void operator()(const f32x4 (&acc)[2][2][4][2], const Unit& u, int wr, int wc, int fr, int fq) const {
;     ...
;             for (int mi = 0; mi < 4; ++mi) { const size_t ro = (size_t)(u.pm * BM + ai * HALF + wr * 64 + mi * 16 + fr) * 1024 + col0;
; #pragma unroll
;                 for (int bj = 0; bj < 2; ++bj) { const u32x4 w = xw[mi][bj];
;                     const f32x4 x0 = (f32x4){__uint_as_float(w.x << 16), __uint_as_float(w.x & 0xffff0000u), __uint_as_float(w.y << 16), __uint_as_float(w.y & 0xffff0000u)};
;                     const f32x4 x1 = (f32x4){__uint_as_float(w.z << 16), __uint_as_float(w.z & 0xffff0000u), __uint_as_float(w.w << 16), __uint_as_float(w.w & 0xffff0000u)};
;                     const f32x4 v0 = x0 + gv[bj][0] * acc[ai][bj][mi][0], v1 = x1 + gv[bj][1] * acc[ai][bj][mi][1];
;                     if (l0) { u32x4 o; o.x = cvt_pk_bf16(v0[0], v0[1]); o.y = cvt_pk_bf16(v0[2], v0[3]); o.z = cvt_pk_bf16(v1[0], v1[1]); o.w = cvt_pk_bf16(v1[2], v1[3]);
;                               *(u32x4*)(outb + ro + bj * HALF) = o; }
;                     else { __builtin_nontemporal_store(v0, (f32x4*)(outf + ro + bj * HALF)); __builtin_nontemporal_store(v1, (f32x4*)(outf + ro + bj * HALF + 4)); }
.LBB0_620:
	s_nop 1
	v_lshlrev_b32_e32 v136, 16, v168
	v_and_b32_e32 v137, 0xffff0000, v168
	v_lshlrev_b32_e32 v138, 16, v169
	v_and_b32_e32 v139, 0xffff0000, v169
	v_lshlrev_b32_e32 v140, 16, v170
	v_and_b32_e32 v141, 0xffff0000, v170
	v_lshlrev_b32_e32 v142, 16, v171
	v_and_b32_e32 v143, 0xffff0000, v171
	v_pk_fma_f32 v[134:135], v[134:135], v[74:75], v[138:139]
	v_pk_fma_f32 v[132:133], v[132:133], v[72:73], v[136:137]
	v_pk_fma_f32 v[130:131], v[130:131], v[70:71], v[142:143]
	v_pk_fma_f32 v[128:129], v[128:129], v[68:69], v[140:141]
	s_mov_b64 s[34:35], -1
	s_and_b64 vcc, exec, s[8:9]
	s_cbranch_vccz .LBB0_622
	v_cvt_pk_bf16_f32 v136, v132, v133
	v_cvt_pk_bf16_f32 v137, v134, v135
	v_cvt_pk_bf16_f32 v138, v128, v129
	v_cvt_pk_bf16_f32 v139, v130, v131
	global_store_dwordx4 v[204:205], v[136:139], off offset:256 sc1
	s_mov_b64 s[34:35], 0

; __device__ __forceinline__ unsigned cvt_pk_bf16(float lo, float hi) { unsigned r; asm volatile("v_cvt_pk_bf16_f32 %0, %1, %2" : "=v"(r) : "v"(lo), "v"(hi)); return r; }
;     __device__ __forceinline__ void operator()(const f32x4 (&acc)[2][2][4][2], const Unit& u, int wr, int wc, int fr, int fq) const {
;     ...
;             for (int mi = 0; mi < 4; ++mi) { const size_t ro = (size_t)(u.pm * BM + ai * HALF + wr * 64 + mi * 16 + fr) * 1024 + col0;
; #pragma unroll
;                 for (int bj = 0; bj < 2; ++bj) { const u32x4 w = xw[mi][bj];
;                     const f32x4 x0 = (f32x4){__uint_as_float(w.x << 16), __uint_as_float(w.x & 0xffff0000u), __uint_as_float(w.y << 16), __uint_as_float(w.y & 0xffff0000u)};
;                     const f32x4 x1 = (f32x4){__uint_as_float(w.z << 16), __uint_as_float(w.z & 0xffff0000u), __uint_as_float(w.w << 16), __uint_as_float(w.w & 0xffff0000u)};
;                     const f32x4 v0 = x0 + gv[bj][0] * acc[ai][bj][mi][0], v1 = x1 + gv[bj][1] * acc[ai][bj][mi][1];
;                     if (l0) { u32x4 o; o.x = cvt_pk_bf16(v0[0], v0[1]); o.y = cvt_pk_bf16(v0[2], v0[3]); o.z = cvt_pk_bf16(v1[0], v1[1]); o.w = cvt_pk_bf16(v1[2], v1[3]);
;                               *(u32x4*)(outb + ro + bj * HALF) = o; }
;                     else { __builtin_nontemporal_store(v0, (f32x4*)(outf + ro + bj * HALF)); __builtin_nontemporal_store(v1, (f32x4*)(outf + ro + bj * HALF + 4)); }
.LBB0_624:
	s_nop 1
	v_lshlrev_b64 v[128:129], 10, v[202:203]
	v_lshl_add_u64 v[130:131], v[128:129], 0, v[192:193]
	v_lshlrev_b32_e32 v128, 16, v164
	v_and_b32_e32 v129, 0xffff0000, v164
	v_lshlrev_b32_e32 v132, 16, v165
	v_and_b32_e32 v133, 0xffff0000, v165
	v_lshlrev_b32_e32 v134, 16, v166
	v_and_b32_e32 v135, 0xffff0000, v166
	v_lshlrev_b32_e32 v136, 16, v167
	v_and_b32_e32 v137, 0xffff0000, v167
	v_pk_fma_f32 v[126:127], v[126:127], v[86:87], v[132:133]
	v_pk_fma_f32 v[124:125], v[124:125], v[84:85], v[128:129]
	v_pk_fma_f32 v[122:123], v[122:123], v[82:83], v[136:137]
	v_pk_fma_f32 v[120:121], v[120:121], v[80:81], v[134:135]
	s_mov_b64 s[34:35], -1
	s_and_b64 vcc, exec, s[8:9]
	v_lshl_add_u64 v[128:129], v[130:131], 1, s[58:59]
	s_cbranch_vccz .LBB0_626
	v_cvt_pk_bf16_f32 v132, v124, v125
	v_cvt_pk_bf16_f32 v133, v126, v127
	v_cvt_pk_bf16_f32 v134, v120, v121
	v_cvt_pk_bf16_f32 v135, v122, v123
	global_store_dwordx4 v[128:129], v[132:135], off sc1
	s_mov_b64 s[34:35], 0

; __device__ __forceinline__ unsigned cvt_pk_bf16(float lo, float hi) { unsigned r; asm volatile("v_cvt_pk_bf16_f32 %0, %1, %2" : "=v"(r) : "v"(lo), "v"(hi)); return r; }
;     __device__ __forceinline__ void operator()(const f32x4 (&acc)[2][2][4][2], const Unit& u, int wr, int wc, int fr, int fq) const {
;     ...
;             for (int mi = 0; mi < 4; ++mi) { const size_t ro = (size_t)(u.pm * BM + ai * HALF + wr * 64 + mi * 16 + fr) * 1024 + col0;
; #pragma unroll
;                 for (int bj = 0; bj < 2; ++bj) { const u32x4 w = xw[mi][bj];
;                     const f32x4 x0 = (f32x4){__uint_as_float(w.x << 16), __uint_as_float(w.x & 0xffff0000u), __uint_as_float(w.y << 16), __uint_as_float(w.y & 0xffff0000u)};
;                     const f32x4 x1 = (f32x4){__uint_as_float(w.z << 16), __uint_as_float(w.z & 0xffff0000u), __uint_as_float(w.w << 16), __uint_as_float(w.w & 0xffff0000u)};
;                     const f32x4 v0 = x0 + gv[bj][0] * acc[ai][bj][mi][0], v1 = x1 + gv[bj][1] * acc[ai][bj][mi][1];
;                     if (l0) { u32x4 o; o.x = cvt_pk_bf16(v0[0], v0[1]); o.y = cvt_pk_bf16(v0[2], v0[3]); o.z = cvt_pk_bf16(v1[0], v1[1]); o.w = cvt_pk_bf16(v1[2], v1[3]);
;                               *(u32x4*)(outb + ro + bj * HALF) = o; }
;                     else { __builtin_nontemporal_store(v0, (f32x4*)(outf + ro + bj * HALF)); __builtin_nontemporal_store(v1, (f32x4*)(outf + ro + bj * HALF + 4)); }
.LBB0_628:
	s_nop 1
	v_lshlrev_b32_e32 v120, 16, v160
	v_and_b32_e32 v121, 0xffff0000, v160
	v_lshlrev_b32_e32 v122, 16, v161
	v_and_b32_e32 v123, 0xffff0000, v161
	v_lshlrev_b32_e32 v124, 16, v162
	v_and_b32_e32 v125, 0xffff0000, v162
	v_lshlrev_b32_e32 v126, 16, v163
	v_and_b32_e32 v127, 0xffff0000, v163
	v_pk_fma_f32 v[118:119], v[118:119], v[74:75], v[122:123]
	v_pk_fma_f32 v[116:117], v[116:117], v[72:73], v[120:121]
	v_pk_fma_f32 v[114:115], v[114:115], v[70:71], v[126:127]
	v_pk_fma_f32 v[112:113], v[112:113], v[68:69], v[124:125]
	s_mov_b64 s[34:35], -1
	s_and_b64 vcc, exec, s[8:9]
	s_cbranch_vccz .LBB0_630
	v_cvt_pk_bf16_f32 v120, v116, v117
	v_cvt_pk_bf16_f32 v121, v118, v119
	v_cvt_pk_bf16_f32 v122, v112, v113
	v_cvt_pk_bf16_f32 v123, v114, v115
	global_store_dwordx4 v[128:129], v[120:123], off offset:256 sc1
	s_mov_b64 s[34:35], 0

; __device__ __forceinline__ unsigned cvt_pk_bf16(float lo, float hi) { unsigned r; asm volatile("v_cvt_pk_bf16_f32 %0, %1, %2" : "=v"(r) : "v"(lo), "v"(hi)); return r; }
;     __device__ __forceinline__ void operator()(const f32x4 (&acc)[2][2][4][2], const Unit& u, int wr, int wc, int fr, int fq) const {
;     ...
;             for (int mi = 0; mi < 4; ++mi) { const size_t ro = (size_t)(u.pm * BM + ai * HALF + wr * 64 + mi * 16 + fr) * 1024 + col0;
; #pragma unroll
;                 for (int bj = 0; bj < 2; ++bj) { const u32x4 w = xw[mi][bj];
;                     const f32x4 x0 = (f32x4){__uint_as_float(w.x << 16), __uint_as_float(w.x & 0xffff0000u), __uint_as_float(w.y << 16), __uint_as_float(w.y & 0xffff0000u)};
;                     const f32x4 x1 = (f32x4){__uint_as_float(w.z << 16), __uint_as_float(w.z & 0xffff0000u), __uint_as_float(w.w << 16), __uint_as_float(w.w & 0xffff0000u)};
;                     const f32x4 v0 = x0 + gv[bj][0] * acc[ai][bj][mi][0], v1 = x1 + gv[bj][1] * acc[ai][bj][mi][1];
;                     if (l0) { u32x4 o; o.x = cvt_pk_bf16(v0[0], v0[1]); o.y = cvt_pk_bf16(v0[2], v0[3]); o.z = cvt_pk_bf16(v1[0], v1[1]); o.w = cvt_pk_bf16(v1[2], v1[3]);
;                               *(u32x4*)(outb + ro + bj * HALF) = o; }
;                     else { __builtin_nontemporal_store(v0, (f32x4*)(outf + ro + bj * HALF)); __builtin_nontemporal_store(v1, (f32x4*)(outf + ro + bj * HALF + 4)); }
.LBB0_632:
	s_nop 1
	v_lshlrev_b64 v[112:113], 10, v[200:201]
	v_lshl_add_u64 v[114:115], v[112:113], 0, v[192:193]
	v_lshlrev_b32_e32 v112, 16, v156
	v_and_b32_e32 v113, 0xffff0000, v156
	v_lshlrev_b32_e32 v116, 16, v157
	v_and_b32_e32 v117, 0xffff0000, v157
	v_lshlrev_b32_e32 v118, 16, v158
	v_and_b32_e32 v119, 0xffff0000, v158
	v_lshlrev_b32_e32 v120, 16, v159
	v_and_b32_e32 v121, 0xffff0000, v159
	v_pk_fma_f32 v[110:111], v[110:111], v[86:87], v[116:117]
	v_pk_fma_f32 v[108:109], v[108:109], v[84:85], v[112:113]
	v_pk_fma_f32 v[106:107], v[106:107], v[82:83], v[120:121]
	v_pk_fma_f32 v[104:105], v[104:105], v[80:81], v[118:119]
	s_mov_b64 s[34:35], -1
	s_and_b64 vcc, exec, s[8:9]
	v_lshl_add_u64 v[112:113], v[114:115], 1, s[58:59]
	s_cbranch_vccz .LBB0_634
	v_cvt_pk_bf16_f32 v116, v108, v109
	v_cvt_pk_bf16_f32 v117, v110, v111
	v_cvt_pk_bf16_f32 v118, v104, v105
	v_cvt_pk_bf16_f32 v119, v106, v107
	global_store_dwordx4 v[112:113], v[116:119], off sc1
	s_mov_b64 s[34:35], 0

; __device__ __forceinline__ unsigned cvt_pk_bf16(float lo, float hi) { unsigned r; asm volatile("v_cvt_pk_bf16_f32 %0, %1, %2" : "=v"(r) : "v"(lo), "v"(hi)); return r; }
;     __device__ __forceinline__ void operator()(const f32x4 (&acc)[2][2][4][2], const Unit& u, int wr, int wc, int fr, int fq) const {
;     ...
;             for (int mi = 0; mi < 4; ++mi) { const size_t ro = (size_t)(u.pm * BM + ai * HALF + wr * 64 + mi * 16 + fr) * 1024 + col0;
; #pragma unroll
;                 for (int bj = 0; bj < 2; ++bj) { const u32x4 w = xw[mi][bj];
;                     const f32x4 x0 = (f32x4){__uint_as_float(w.x << 16), __uint_as_float(w.x & 0xffff0000u), __uint_as_float(w.y << 16), __uint_as_float(w.y & 0xffff0000u)};
;                     const f32x4 x1 = (f32x4){__uint_as_float(w.z << 16), __uint_as_float(w.z & 0xffff0000u), __uint_as_float(w.w << 16), __uint_as_float(w.w & 0xffff0000u)};
;                     const f32x4 v0 = x0 + gv[bj][0] * acc[ai][bj][mi][0], v1 = x1 + gv[bj][1] * acc[ai][bj][mi][1];
;                     if (l0) { u32x4 o; o.x = cvt_pk_bf16(v0[0], v0[1]); o.y = cvt_pk_bf16(v0[2], v0[3]); o.z = cvt_pk_bf16(v1[0], v1[1]); o.w = cvt_pk_bf16(v1[2], v1[3]);
;                               *(u32x4*)(outb + ro + bj * HALF) = o; }
;                     else { __builtin_nontemporal_store(v0, (f32x4*)(outf + ro + bj * HALF)); __builtin_nontemporal_store(v1, (f32x4*)(outf + ro + bj * HALF + 4)); }
.LBB0_636:
	s_nop 1
	v_lshlrev_b32_e32 v104, 16, v152
	v_and_b32_e32 v105, 0xffff0000, v152
	v_lshlrev_b32_e32 v106, 16, v153
	v_and_b32_e32 v107, 0xffff0000, v153
	v_lshlrev_b32_e32 v108, 16, v154
	v_and_b32_e32 v109, 0xffff0000, v154
	v_lshlrev_b32_e32 v110, 16, v155
	v_and_b32_e32 v111, 0xffff0000, v155
	v_pk_fma_f32 v[102:103], v[102:103], v[74:75], v[106:107]
	v_pk_fma_f32 v[100:101], v[100:101], v[72:73], v[104:105]
	v_pk_fma_f32 v[98:99], v[98:99], v[70:71], v[110:111]
	v_pk_fma_f32 v[96:97], v[96:97], v[68:69], v[108:109]
	s_mov_b64 s[34:35], -1
	s_and_b64 vcc, exec, s[8:9]
	s_cbranch_vccz .LBB0_638
	v_cvt_pk_bf16_f32 v104, v100, v101
	v_cvt_pk_bf16_f32 v105, v102, v103
	v_cvt_pk_bf16_f32 v106, v96, v97
	v_cvt_pk_bf16_f32 v107, v98, v99
	global_store_dwordx4 v[112:113], v[104:107], off offset:256 sc1
	s_mov_b64 s[34:35], 0

; __device__ __forceinline__ unsigned cvt_pk_bf16(float lo, float hi) { unsigned r; asm volatile("v_cvt_pk_bf16_f32 %0, %1, %2" : "=v"(r) : "v"(lo), "v"(hi)); return r; }
;     __device__ __forceinline__ void operator()(const f32x4 (&acc)[2][2][4][2], const Unit& u, int wr, int wc, int fr, int fq) const {
;     ...
;             for (int mi = 0; mi < 4; ++mi) { const size_t ro = (size_t)(u.pm * BM + ai * HALF + wr * 64 + mi * 16 + fr) * 1024 + col0;
; #pragma unroll
;                 for (int bj = 0; bj < 2; ++bj) { const u32x4 w = xw[mi][bj];
;                     const f32x4 x0 = (f32x4){__uint_as_float(w.x << 16), __uint_as_float(w.x & 0xffff0000u), __uint_as_float(w.y << 16), __uint_as_float(w.y & 0xffff0000u)};
;                     const f32x4 x1 = (f32x4){__uint_as_float(w.z << 16), __uint_as_float(w.z & 0xffff0000u), __uint_as_float(w.w << 16), __uint_as_float(w.w & 0xffff0000u)};
;                     const f32x4 v0 = x0 + gv[bj][0] * acc[ai][bj][mi][0], v1 = x1 + gv[bj][1] * acc[ai][bj][mi][1];
;                     if (l0) { u32x4 o; o.x = cvt_pk_bf16(v0[0], v0[1]); o.y = cvt_pk_bf16(v0[2], v0[3]); o.z = cvt_pk_bf16(v1[0], v1[1]); o.w = cvt_pk_bf16(v1[2], v1[3]);
;                               *(u32x4*)(outb + ro + bj * HALF) = o; }
;                     else { __builtin_nontemporal_store(v0, (f32x4*)(outf + ro + bj * HALF)); __builtin_nontemporal_store(v1, (f32x4*)(outf + ro + bj * HALF + 4)); }
.LBB0_640:
	s_nop 1
	v_lshlrev_b64 v[96:97], 10, v[198:199]
	v_lshl_add_u64 v[98:99], v[96:97], 0, v[192:193]
	v_lshlrev_b32_e32 v96, 16, v148
	v_and_b32_e32 v97, 0xffff0000, v148
	v_lshlrev_b32_e32 v100, 16, v149
	v_and_b32_e32 v101, 0xffff0000, v149
	v_lshlrev_b32_e32 v102, 16, v150
	v_and_b32_e32 v103, 0xffff0000, v150
	v_lshlrev_b32_e32 v104, 16, v151
	v_and_b32_e32 v105, 0xffff0000, v151
	v_pk_fma_f32 v[94:95], v[94:95], v[86:87], v[100:101]
	v_pk_fma_f32 v[92:93], v[92:93], v[84:85], v[96:97]
	v_pk_fma_f32 v[90:91], v[90:91], v[82:83], v[104:105]
	v_pk_fma_f32 v[88:89], v[88:89], v[80:81], v[102:103]
	s_mov_b64 s[34:35], -1
	s_and_b64 vcc, exec, s[8:9]
	v_lshl_add_u64 v[96:97], v[98:99], 1, s[58:59]
	s_cbranch_vccz .LBB0_642
	v_cvt_pk_bf16_f32 v100, v92, v93
	v_cvt_pk_bf16_f32 v101, v94, v95
	v_cvt_pk_bf16_f32 v102, v88, v89
	v_cvt_pk_bf16_f32 v103, v90, v91
	global_store_dwordx4 v[96:97], v[100:103], off sc1
	s_mov_b64 s[34:35], 0

; __device__ __forceinline__ unsigned cvt_pk_bf16(float lo, float hi) { unsigned r; asm volatile("v_cvt_pk_bf16_f32 %0, %1, %2" : "=v"(r) : "v"(lo), "v"(hi)); return r; }
;     __device__ __forceinline__ void operator()(const f32x4 (&acc)[2][2][4][2], const Unit& u, int wr, int wc, int fr, int fq) const {
;     ...
;             for (int mi = 0; mi < 4; ++mi) { const size_t ro = (size_t)(u.pm * BM + ai * HALF + wr * 64 + mi * 16 + fr) * 1024 + col0;
; #pragma unroll
;                 for (int bj = 0; bj < 2; ++bj) { const u32x4 w = xw[mi][bj];
;                     const f32x4 x0 = (f32x4){__uint_as_float(w.x << 16), __uint_as_float(w.x & 0xffff0000u), __uint_as_float(w.y << 16), __uint_as_float(w.y & 0xffff0000u)};
;                     const f32x4 x1 = (f32x4){__uint_as_float(w.z << 16), __uint_as_float(w.z & 0xffff0000u), __uint_as_float(w.w << 16), __uint_as_float(w.w & 0xffff0000u)};
;                     const f32x4 v0 = x0 + gv[bj][0] * acc[ai][bj][mi][0], v1 = x1 + gv[bj][1] * acc[ai][bj][mi][1];
;                     if (l0) { u32x4 o; o.x = cvt_pk_bf16(v0[0], v0[1]); o.y = cvt_pk_bf16(v0[2], v0[3]); o.z = cvt_pk_bf16(v1[0], v1[1]); o.w = cvt_pk_bf16(v1[2], v1[3]);
;                               *(u32x4*)(outb + ro + bj * HALF) = o; }
;                     else { __builtin_nontemporal_store(v0, (f32x4*)(outf + ro + bj * HALF)); __builtin_nontemporal_store(v1, (f32x4*)(outf + ro + bj * HALF + 4)); }
.LBB0_644:
	s_nop 1
	v_lshlrev_b32_e32 v88, 16, v144
	v_and_b32_e32 v89, 0xffff0000, v144
	v_lshlrev_b32_e32 v90, 16, v145
	v_and_b32_e32 v91, 0xffff0000, v145
	v_lshlrev_b32_e32 v92, 16, v146
	v_and_b32_e32 v93, 0xffff0000, v146
	v_lshlrev_b32_e32 v94, 16, v147
	v_and_b32_e32 v95, 0xffff0000, v147
	v_pk_fma_f32 v[78:79], v[78:79], v[74:75], v[90:91]
	v_pk_fma_f32 v[76:77], v[76:77], v[72:73], v[88:89]
	v_pk_fma_f32 v[66:67], v[66:67], v[70:71], v[94:95]
	v_pk_fma_f32 v[64:65], v[64:65], v[68:69], v[92:93]
	s_mov_b64 s[34:35], -1
	s_and_b64 vcc, exec, s[8:9]
	s_cbranch_vccz .LBB0_646
	v_cvt_pk_bf16_f32 v88, v76, v77
	v_cvt_pk_bf16_f32 v89, v78, v79
	v_cvt_pk_bf16_f32 v90, v64, v65
	v_cvt_pk_bf16_f32 v91, v66, v67
	global_store_dwordx4 v[96:97], v[88:91], off offset:256 sc1
	s_mov_b64 s[34:35], 0

; __device__ __forceinline__ unsigned cvt_pk_bf16(float lo, float hi) { unsigned r; asm volatile("v_cvt_pk_bf16_f32 %0, %1, %2" : "=v"(r) : "v"(lo), "v"(hi)); return r; }
;     __device__ __forceinline__ void operator()(const f32x4 (&acc)[2][2][4][2], const Unit& u, int wr, int wc, int fr, int fq) const {
;     ...
;         for (int ai = 0; ai < 2; ++ai) {
;             u32x4 xw[4][2];
; #pragma unroll
;             for (int mi = 0; mi < 4; ++mi) { const bf16_t* bp = xb + (size_t)(u.pm * BM + ai * HALF + wr * 64 + mi * 16 + fr) * 1024 + col0;
; #pragma unroll
;                 for (int bj = 0; bj < 2; ++bj) xw[mi][bj] = __builtin_nontemporal_load((const u32x4*)(bp + bj * HALF)); }
; #pragma unroll
;             for (int mi = 0; mi < 4; ++mi) { const size_t ro = (size_t)(u.pm * BM + ai * HALF + wr * 64 + mi * 16 + fr) * 1024 + col0;
; #pragma unroll
;                 for (int bj = 0; bj < 2; ++bj) { const u32x4 w = xw[mi][bj];
;                     const f32x4 x0 = (f32x4){__uint_as_float(w.x << 16), __uint_as_float(w.x & 0xffff0000u), __uint_as_float(w.y << 16), __uint_as_float(w.y & 0xffff0000u)};
;                     const f32x4 x1 = (f32x4){__uint_as_float(w.z << 16), __uint_as_float(w.z & 0xffff0000u), __uint_as_float(w.w << 16), __uint_as_float(w.w & 0xffff0000u)};
;                     const f32x4 v0 = x0 + gv[bj][0] * acc[ai][bj][mi][0], v1 = x1 + gv[bj][1] * acc[ai][bj][mi][1];
;                     if (l0) { u32x4 o; o.x = cvt_pk_bf16(v0[0], v0[1]); o.y = cvt_pk_bf16(v0[2], v0[3]); o.z = cvt_pk_bf16(v1[0], v1[1]); o.w = cvt_pk_bf16(v1[2], v1[3]);
;                               *(u32x4*)(outb + ro + bj * HALF) = o; }
;                     else { __builtin_nontemporal_store(v0, (f32x4*)(outf + ro + bj * HALF)); __builtin_nontemporal_store(v1, (f32x4*)(outf + ro + bj * HALF + 4)); }
.LBB0_648:
	v_add_u32_e32 v114, 0x80, v196
	v_ashrrev_i32_e32 v115, 31, v114
	v_lshlrev_b64 v[64:65], 11, v[114:115]
	v_add_u32_e32 v112, 0x90, v196
	v_lshl_add_u64 v[64:65], v[194:195], 0, v[64:65]
	v_ashrrev_i32_e32 v113, 31, v112
	global_load_dwordx4 v[116:119], v[64:65], off nt
	global_load_dwordx4 v[104:107], v[64:65], off offset:256 nt
	v_lshlrev_b64 v[64:65], 11, v[112:113]
	v_add_u32_e32 v110, 0xa0, v196
	v_lshl_add_u64 v[64:65], v[194:195], 0, v[64:65]
	v_ashrrev_i32_e32 v111, 31, v110
	global_load_dwordx4 v[100:103], v[64:65], off nt
	global_load_dwordx4 v[96:99], v[64:65], off offset:256 nt
	v_lshlrev_b64 v[64:65], 11, v[110:111]
	v_add_u32_e32 v108, 0xb0, v196
	v_lshl_add_u64 v[64:65], v[194:195], 0, v[64:65]
	v_ashrrev_i32_e32 v109, 31, v108
	global_load_dwordx4 v[92:95], v[64:65], off nt
	global_load_dwordx4 v[88:91], v[64:65], off offset:256 nt
	v_lshlrev_b64 v[64:65], 11, v[108:109]
	v_lshl_add_u64 v[64:65], v[194:195], 0, v[64:65]
	global_load_dwordx4 v[76:79], v[64:65], off nt
	s_nop 0
	global_load_dwordx4 v[64:67], v[64:65], off offset:256 nt
	v_lshlrev_b64 v[114:115], 10, v[114:115]
	v_lshl_add_u64 v[114:115], v[114:115], 0, v[192:193]
	s_mov_b64 s[34:35], -1
	s_and_b64 vcc, exec, s[8:9]
	s_waitcnt vmcnt(7)
	v_lshlrev_b32_e32 v120, 16, v116
	v_and_b32_e32 v121, 0xffff0000, v116
	v_lshlrev_b32_e32 v116, 16, v117
	v_and_b32_e32 v117, 0xffff0000, v117
	v_lshlrev_b32_e32 v122, 16, v118
	v_and_b32_e32 v123, 0xffff0000, v118
	v_lshlrev_b32_e32 v118, 16, v119
	v_and_b32_e32 v119, 0xffff0000, v119
	v_pk_fma_f32 v[62:63], v[62:63], v[86:87], v[116:117]
	v_pk_fma_f32 v[60:61], v[60:61], v[84:85], v[120:121]
	v_pk_fma_f32 v[58:59], v[58:59], v[82:83], v[118:119]
	v_pk_fma_f32 v[56:57], v[56:57], v[80:81], v[122:123]
	v_lshl_add_u64 v[116:117], v[114:115], 1, s[58:59]
	s_cbranch_vccz .LBB0_650
	v_cvt_pk_bf16_f32 v118, v60, v61
	v_cvt_pk_bf16_f32 v119, v62, v63
	v_cvt_pk_bf16_f32 v120, v56, v57
	v_cvt_pk_bf16_f32 v121, v58, v59
	global_store_dwordx4 v[116:117], v[118:121], off sc1
	s_mov_b64 s[34:35], 0

; __device__ __forceinline__ unsigned cvt_pk_bf16(float lo, float hi) { unsigned r; asm volatile("v_cvt_pk_bf16_f32 %0, %1, %2" : "=v"(r) : "v"(lo), "v"(hi)); return r; }
;     __device__ __forceinline__ void operator()(const f32x4 (&acc)[2][2][4][2], const Unit& u, int wr, int wc, int fr, int fq) const {
;     ...
;             for (int mi = 0; mi < 4; ++mi) { const size_t ro = (size_t)(u.pm * BM + ai * HALF + wr * 64 + mi * 16 + fr) * 1024 + col0;
; #pragma unroll
;                 for (int bj = 0; bj < 2; ++bj) { const u32x4 w = xw[mi][bj];
;                     const f32x4 x0 = (f32x4){__uint_as_float(w.x << 16), __uint_as_float(w.x & 0xffff0000u), __uint_as_float(w.y << 16), __uint_as_float(w.y & 0xffff0000u)};
;                     const f32x4 x1 = (f32x4){__uint_as_float(w.z << 16), __uint_as_float(w.z & 0xffff0000u), __uint_as_float(w.w << 16), __uint_as_float(w.w & 0xffff0000u)};
;                     const f32x4 v0 = x0 + gv[bj][0] * acc[ai][bj][mi][0], v1 = x1 + gv[bj][1] * acc[ai][bj][mi][1];
;                     if (l0) { u32x4 o; o.x = cvt_pk_bf16(v0[0], v0[1]); o.y = cvt_pk_bf16(v0[2], v0[3]); o.z = cvt_pk_bf16(v1[0], v1[1]); o.w = cvt_pk_bf16(v1[2], v1[3]);
;                               *(u32x4*)(outb + ro + bj * HALF) = o; }
;                     else { __builtin_nontemporal_store(v0, (f32x4*)(outf + ro + bj * HALF)); __builtin_nontemporal_store(v1, (f32x4*)(outf + ro + bj * HALF + 4)); }
.LBB0_652:
	s_waitcnt vmcnt(6)
	s_nop 0
	v_lshlrev_b32_e32 v56, 16, v104
	v_and_b32_e32 v57, 0xffff0000, v104
	v_lshlrev_b32_e32 v58, 16, v105
	v_and_b32_e32 v59, 0xffff0000, v105
	v_lshlrev_b32_e32 v60, 16, v106
	v_and_b32_e32 v61, 0xffff0000, v106
	v_lshlrev_b32_e32 v62, 16, v107
	v_and_b32_e32 v63, 0xffff0000, v107
	v_pk_fma_f32 v[54:55], v[54:55], v[74:75], v[58:59]
	v_pk_fma_f32 v[52:53], v[52:53], v[72:73], v[56:57]
	v_pk_fma_f32 v[50:51], v[50:51], v[70:71], v[62:63]
	v_pk_fma_f32 v[48:49], v[48:49], v[68:69], v[60:61]
	s_mov_b64 s[34:35], -1
	s_and_b64 vcc, exec, s[8:9]
	s_cbranch_vccz .LBB0_654
	v_cvt_pk_bf16_f32 v56, v52, v53
	v_cvt_pk_bf16_f32 v57, v54, v55
	v_cvt_pk_bf16_f32 v58, v48, v49
	v_cvt_pk_bf16_f32 v59, v50, v51
	global_store_dwordx4 v[116:117], v[56:59], off offset:256 sc1
	s_mov_b64 s[34:35], 0

; __device__ __forceinline__ unsigned cvt_pk_bf16(float lo, float hi) { unsigned r; asm volatile("v_cvt_pk_bf16_f32 %0, %1, %2" : "=v"(r) : "v"(lo), "v"(hi)); return r; }
;     __device__ __forceinline__ void operator()(const f32x4 (&acc)[2][2][4][2], const Unit& u, int wr, int wc, int fr, int fq) const {
;     ...
;             for (int mi = 0; mi < 4; ++mi) { const size_t ro = (size_t)(u.pm * BM + ai * HALF + wr * 64 + mi * 16 + fr) * 1024 + col0;
; #pragma unroll
;                 for (int bj = 0; bj < 2; ++bj) { const u32x4 w = xw[mi][bj];
;                     const f32x4 x0 = (f32x4){__uint_as_float(w.x << 16), __uint_as_float(w.x & 0xffff0000u), __uint_as_float(w.y << 16), __uint_as_float(w.y & 0xffff0000u)};
;                     const f32x4 x1 = (f32x4){__uint_as_float(w.z << 16), __uint_as_float(w.z & 0xffff0000u), __uint_as_float(w.w << 16), __uint_as_float(w.w & 0xffff0000u)};
;                     const f32x4 v0 = x0 + gv[bj][0] * acc[ai][bj][mi][0], v1 = x1 + gv[bj][1] * acc[ai][bj][mi][1];
;                     if (l0) { u32x4 o; o.x = cvt_pk_bf16(v0[0], v0[1]); o.y = cvt_pk_bf16(v0[2], v0[3]); o.z = cvt_pk_bf16(v1[0], v1[1]); o.w = cvt_pk_bf16(v1[2], v1[3]);
;                               *(u32x4*)(outb + ro + bj * HALF) = o; }
;                     else { __builtin_nontemporal_store(v0, (f32x4*)(outf + ro + bj * HALF)); __builtin_nontemporal_store(v1, (f32x4*)(outf + ro + bj * HALF + 4)); }
.LBB0_656:
	s_nop 1
	v_lshlrev_b64 v[48:49], 10, v[112:113]
	v_lshl_add_u64 v[50:51], v[48:49], 0, v[192:193]
	s_waitcnt vmcnt(5)
	v_lshlrev_b32_e32 v48, 16, v100
	v_and_b32_e32 v49, 0xffff0000, v100
	v_lshlrev_b32_e32 v52, 16, v101
	v_and_b32_e32 v53, 0xffff0000, v101
	v_lshlrev_b32_e32 v54, 16, v102
	v_and_b32_e32 v55, 0xffff0000, v102
	v_lshlrev_b32_e32 v56, 16, v103
	v_and_b32_e32 v57, 0xffff0000, v103
	v_pk_fma_f32 v[46:47], v[46:47], v[86:87], v[52:53]
	v_pk_fma_f32 v[44:45], v[44:45], v[84:85], v[48:49]
	v_pk_fma_f32 v[42:43], v[42:43], v[82:83], v[56:57]
	v_pk_fma_f32 v[40:41], v[40:41], v[80:81], v[54:55]
	s_mov_b64 s[34:35], -1
	s_and_b64 vcc, exec, s[8:9]
	v_lshl_add_u64 v[48:49], v[50:51], 1, s[58:59]
	s_cbranch_vccz .LBB0_658
	v_cvt_pk_bf16_f32 v52, v44, v45
	v_cvt_pk_bf16_f32 v53, v46, v47
	v_cvt_pk_bf16_f32 v54, v40, v41
	v_cvt_pk_bf16_f32 v55, v42, v43
	global_store_dwordx4 v[48:49], v[52:55], off sc1
	s_mov_b64 s[34:35], 0

; __device__ __forceinline__ unsigned cvt_pk_bf16(float lo, float hi) { unsigned r; asm volatile("v_cvt_pk_bf16_f32 %0, %1, %2" : "=v"(r) : "v"(lo), "v"(hi)); return r; }
;     __device__ __forceinline__ void operator()(const f32x4 (&acc)[2][2][4][2], const Unit& u, int wr, int wc, int fr, int fq) const {
;     ...
;             for (int mi = 0; mi < 4; ++mi) { const size_t ro = (size_t)(u.pm * BM + ai * HALF + wr * 64 + mi * 16 + fr) * 1024 + col0;
; #pragma unroll
;                 for (int bj = 0; bj < 2; ++bj) { const u32x4 w = xw[mi][bj];
;                     const f32x4 x0 = (f32x4){__uint_as_float(w.x << 16), __uint_as_float(w.x & 0xffff0000u), __uint_as_float(w.y << 16), __uint_as_float(w.y & 0xffff0000u)};
;                     const f32x4 x1 = (f32x4){__uint_as_float(w.z << 16), __uint_as_float(w.z & 0xffff0000u), __uint_as_float(w.w << 16), __uint_as_float(w.w & 0xffff0000u)};
;                     const f32x4 v0 = x0 + gv[bj][0] * acc[ai][bj][mi][0], v1 = x1 + gv[bj][1] * acc[ai][bj][mi][1];
;                     if (l0) { u32x4 o; o.x = cvt_pk_bf16(v0[0], v0[1]); o.y = cvt_pk_bf16(v0[2], v0[3]); o.z = cvt_pk_bf16(v1[0], v1[1]); o.w = cvt_pk_bf16(v1[2], v1[3]);
;                               *(u32x4*)(outb + ro + bj * HALF) = o; }
;                     else { __builtin_nontemporal_store(v0, (f32x4*)(outf + ro + bj * HALF)); __builtin_nontemporal_store(v1, (f32x4*)(outf + ro + bj * HALF + 4)); }
.LBB0_660:
	s_waitcnt vmcnt(4)
	s_nop 0
	v_lshlrev_b32_e32 v40, 16, v96
	v_and_b32_e32 v41, 0xffff0000, v96
	v_lshlrev_b32_e32 v42, 16, v97
	v_and_b32_e32 v43, 0xffff0000, v97
	v_lshlrev_b32_e32 v44, 16, v98
	v_and_b32_e32 v45, 0xffff0000, v98
	v_lshlrev_b32_e32 v46, 16, v99
	v_and_b32_e32 v47, 0xffff0000, v99
	v_pk_fma_f32 v[38:39], v[38:39], v[74:75], v[42:43]
	v_pk_fma_f32 v[36:37], v[36:37], v[72:73], v[40:41]
	v_pk_fma_f32 v[34:35], v[34:35], v[70:71], v[46:47]
	v_pk_fma_f32 v[32:33], v[32:33], v[68:69], v[44:45]
	s_mov_b64 s[34:35], -1
	s_and_b64 vcc, exec, s[8:9]
	s_cbranch_vccz .LBB0_662
	v_cvt_pk_bf16_f32 v40, v36, v37
	v_cvt_pk_bf16_f32 v41, v38, v39
	v_cvt_pk_bf16_f32 v42, v32, v33
	v_cvt_pk_bf16_f32 v43, v34, v35
	global_store_dwordx4 v[48:49], v[40:43], off offset:256 sc1
	s_mov_b64 s[34:35], 0

; __device__ __forceinline__ unsigned cvt_pk_bf16(float lo, float hi) { unsigned r; asm volatile("v_cvt_pk_bf16_f32 %0, %1, %2" : "=v"(r) : "v"(lo), "v"(hi)); return r; }
;     __device__ __forceinline__ void operator()(const f32x4 (&acc)[2][2][4][2], const Unit& u, int wr, int wc, int fr, int fq) const {
;     ...
;             for (int mi = 0; mi < 4; ++mi) { const size_t ro = (size_t)(u.pm * BM + ai * HALF + wr * 64 + mi * 16 + fr) * 1024 + col0;
; #pragma unroll
;                 for (int bj = 0; bj < 2; ++bj) { const u32x4 w = xw[mi][bj];
;                     const f32x4 x0 = (f32x4){__uint_as_float(w.x << 16), __uint_as_float(w.x & 0xffff0000u), __uint_as_float(w.y << 16), __uint_as_float(w.y & 0xffff0000u)};
;                     const f32x4 x1 = (f32x4){__uint_as_float(w.z << 16), __uint_as_float(w.z & 0xffff0000u), __uint_as_float(w.w << 16), __uint_as_float(w.w & 0xffff0000u)};
;                     const f32x4 v0 = x0 + gv[bj][0] * acc[ai][bj][mi][0], v1 = x1 + gv[bj][1] * acc[ai][bj][mi][1];
;                     if (l0) { u32x4 o; o.x = cvt_pk_bf16(v0[0], v0[1]); o.y = cvt_pk_bf16(v0[2], v0[3]); o.z = cvt_pk_bf16(v1[0], v1[1]); o.w = cvt_pk_bf16(v1[2], v1[3]);
;                               *(u32x4*)(outb + ro + bj * HALF) = o; }
;                     else { __builtin_nontemporal_store(v0, (f32x4*)(outf + ro + bj * HALF)); __builtin_nontemporal_store(v1, (f32x4*)(outf + ro + bj * HALF + 4)); }
.LBB0_664:
	s_nop 1
	v_lshlrev_b64 v[32:33], 10, v[110:111]
	v_lshl_add_u64 v[34:35], v[32:33], 0, v[192:193]
	s_waitcnt vmcnt(3)
	v_lshlrev_b32_e32 v32, 16, v92
	v_and_b32_e32 v33, 0xffff0000, v92
	v_lshlrev_b32_e32 v36, 16, v93
	v_and_b32_e32 v37, 0xffff0000, v93
	v_lshlrev_b32_e32 v38, 16, v94
	v_and_b32_e32 v39, 0xffff0000, v94
	v_lshlrev_b32_e32 v40, 16, v95
	v_and_b32_e32 v41, 0xffff0000, v95
	v_pk_fma_f32 v[30:31], v[30:31], v[86:87], v[36:37]
	v_pk_fma_f32 v[28:29], v[28:29], v[84:85], v[32:33]
	v_pk_fma_f32 v[26:27], v[26:27], v[82:83], v[40:41]
	v_pk_fma_f32 v[24:25], v[24:25], v[80:81], v[38:39]
	s_mov_b64 s[34:35], -1
	s_and_b64 vcc, exec, s[8:9]
	v_lshl_add_u64 v[32:33], v[34:35], 1, s[58:59]
	s_cbranch_vccz .LBB0_666
	v_cvt_pk_bf16_f32 v36, v28, v29
	v_cvt_pk_bf16_f32 v37, v30, v31
	v_cvt_pk_bf16_f32 v38, v24, v25
	v_cvt_pk_bf16_f32 v39, v26, v27
	global_store_dwordx4 v[32:33], v[36:39], off sc1
	s_mov_b64 s[34:35], 0

; __device__ __forceinline__ unsigned cvt_pk_bf16(float lo, float hi) { unsigned r; asm volatile("v_cvt_pk_bf16_f32 %0, %1, %2" : "=v"(r) : "v"(lo), "v"(hi)); return r; }
;     __device__ __forceinline__ void operator()(const f32x4 (&acc)[2][2][4][2], const Unit& u, int wr, int wc, int fr, int fq) const {
;     ...
;             for (int mi = 0; mi < 4; ++mi) { const size_t ro = (size_t)(u.pm * BM + ai * HALF + wr * 64 + mi * 16 + fr) * 1024 + col0;
; #pragma unroll
;                 for (int bj = 0; bj < 2; ++bj) { const u32x4 w = xw[mi][bj];
;                     const f32x4 x0 = (f32x4){__uint_as_float(w.x << 16), __uint_as_float(w.x & 0xffff0000u), __uint_as_float(w.y << 16), __uint_as_float(w.y & 0xffff0000u)};
;                     const f32x4 x1 = (f32x4){__uint_as_float(w.z << 16), __uint_as_float(w.z & 0xffff0000u), __uint_as_float(w.w << 16), __uint_as_float(w.w & 0xffff0000u)};
;                     const f32x4 v0 = x0 + gv[bj][0] * acc[ai][bj][mi][0], v1 = x1 + gv[bj][1] * acc[ai][bj][mi][1];
;                     if (l0) { u32x4 o; o.x = cvt_pk_bf16(v0[0], v0[1]); o.y = cvt_pk_bf16(v0[2], v0[3]); o.z = cvt_pk_bf16(v1[0], v1[1]); o.w = cvt_pk_bf16(v1[2], v1[3]);
;                               *(u32x4*)(outb + ro + bj * HALF) = o; }
;                     else { __builtin_nontemporal_store(v0, (f32x4*)(outf + ro + bj * HALF)); __builtin_nontemporal_store(v1, (f32x4*)(outf + ro + bj * HALF + 4)); }
.LBB0_668:
	s_waitcnt vmcnt(2)
	s_nop 0
	v_lshlrev_b32_e32 v24, 16, v88
	v_and_b32_e32 v25, 0xffff0000, v88
	v_lshlrev_b32_e32 v26, 16, v89
	v_and_b32_e32 v27, 0xffff0000, v89
	v_lshlrev_b32_e32 v28, 16, v90
	v_and_b32_e32 v29, 0xffff0000, v90
	v_lshlrev_b32_e32 v30, 16, v91
	v_and_b32_e32 v31, 0xffff0000, v91
	v_pk_fma_f32 v[22:23], v[22:23], v[74:75], v[26:27]
	v_pk_fma_f32 v[20:21], v[20:21], v[72:73], v[24:25]
	v_pk_fma_f32 v[18:19], v[18:19], v[70:71], v[30:31]
	v_pk_fma_f32 v[16:17], v[16:17], v[68:69], v[28:29]
	s_mov_b64 s[34:35], -1
	s_and_b64 vcc, exec, s[8:9]
	s_cbranch_vccz .LBB0_670
	v_cvt_pk_bf16_f32 v24, v20, v21
	v_cvt_pk_bf16_f32 v25, v22, v23
	v_cvt_pk_bf16_f32 v26, v16, v17
	v_cvt_pk_bf16_f32 v27, v18, v19
	global_store_dwordx4 v[32:33], v[24:27], off offset:256 sc1
	s_mov_b64 s[34:35], 0

; __device__ __forceinline__ unsigned cvt_pk_bf16(float lo, float hi) { unsigned r; asm volatile("v_cvt_pk_bf16_f32 %0, %1, %2" : "=v"(r) : "v"(lo), "v"(hi)); return r; }
;     __device__ __forceinline__ void operator()(const f32x4 (&acc)[2][2][4][2], const Unit& u, int wr, int wc, int fr, int fq) const {
;     ...
;             for (int mi = 0; mi < 4; ++mi) { const size_t ro = (size_t)(u.pm * BM + ai * HALF + wr * 64 + mi * 16 + fr) * 1024 + col0;
; #pragma unroll
;                 for (int bj = 0; bj < 2; ++bj) { const u32x4 w = xw[mi][bj];
;                     const f32x4 x0 = (f32x4){__uint_as_float(w.x << 16), __uint_as_float(w.x & 0xffff0000u), __uint_as_float(w.y << 16), __uint_as_float(w.y & 0xffff0000u)};
;                     const f32x4 x1 = (f32x4){__uint_as_float(w.z << 16), __uint_as_float(w.z & 0xffff0000u), __uint_as_float(w.w << 16), __uint_as_float(w.w & 0xffff0000u)};
;                     const f32x4 v0 = x0 + gv[bj][0] * acc[ai][bj][mi][0], v1 = x1 + gv[bj][1] * acc[ai][bj][mi][1];
;                     if (l0) { u32x4 o; o.x = cvt_pk_bf16(v0[0], v0[1]); o.y = cvt_pk_bf16(v0[2], v0[3]); o.z = cvt_pk_bf16(v1[0], v1[1]); o.w = cvt_pk_bf16(v1[2], v1[3]);
;                               *(u32x4*)(outb + ro + bj * HALF) = o; }
;                     else { __builtin_nontemporal_store(v0, (f32x4*)(outf + ro + bj * HALF)); __builtin_nontemporal_store(v1, (f32x4*)(outf + ro + bj * HALF + 4)); }
.LBB0_672:
	s_nop 1
	v_lshlrev_b64 v[16:17], 10, v[108:109]
	v_lshl_add_u64 v[18:19], v[16:17], 0, v[192:193]
	s_waitcnt vmcnt(1)
	v_lshlrev_b32_e32 v16, 16, v76
	v_and_b32_e32 v17, 0xffff0000, v76
	v_lshlrev_b32_e32 v20, 16, v77
	v_and_b32_e32 v21, 0xffff0000, v77
	v_lshlrev_b32_e32 v22, 16, v78
	v_and_b32_e32 v23, 0xffff0000, v78
	v_lshlrev_b32_e32 v24, 16, v79
	v_and_b32_e32 v25, 0xffff0000, v79
	v_pk_fma_f32 v[14:15], v[14:15], v[86:87], v[20:21]
	v_pk_fma_f32 v[12:13], v[12:13], v[84:85], v[16:17]
	v_pk_fma_f32 v[10:11], v[10:11], v[82:83], v[24:25]
	v_pk_fma_f32 v[8:9], v[8:9], v[80:81], v[22:23]
	s_mov_b64 s[34:35], -1
	s_and_b64 vcc, exec, s[8:9]
	v_lshl_add_u64 v[16:17], v[18:19], 1, s[58:59]
	s_cbranch_vccz .LBB0_674
	v_cvt_pk_bf16_f32 v20, v12, v13
	v_cvt_pk_bf16_f32 v21, v14, v15
	v_cvt_pk_bf16_f32 v22, v8, v9
	v_cvt_pk_bf16_f32 v23, v10, v11
	global_store_dwordx4 v[16:17], v[20:23], off sc1
	s_mov_b64 s[34:35], 0

; __device__ __forceinline__ unsigned cvt_pk_bf16(float lo, float hi) { unsigned r; asm volatile("v_cvt_pk_bf16_f32 %0, %1, %2" : "=v"(r) : "v"(lo), "v"(hi)); return r; }
;     __device__ __forceinline__ void operator()(const f32x4 (&acc)[2][2][4][2], const Unit& u, int wr, int wc, int fr, int fq) const {
;     ...
;             for (int mi = 0; mi < 4; ++mi) { const size_t ro = (size_t)(u.pm * BM + ai * HALF + wr * 64 + mi * 16 + fr) * 1024 + col0;
; #pragma unroll
;                 for (int bj = 0; bj < 2; ++bj) { const u32x4 w = xw[mi][bj];
;                     const f32x4 x0 = (f32x4){__uint_as_float(w.x << 16), __uint_as_float(w.x & 0xffff0000u), __uint_as_float(w.y << 16), __uint_as_float(w.y & 0xffff0000u)};
;                     const f32x4 x1 = (f32x4){__uint_as_float(w.z << 16), __uint_as_float(w.z & 0xffff0000u), __uint_as_float(w.w << 16), __uint_as_float(w.w & 0xffff0000u)};
;                     const f32x4 v0 = x0 + gv[bj][0] * acc[ai][bj][mi][0], v1 = x1 + gv[bj][1] * acc[ai][bj][mi][1];
;                     if (l0) { u32x4 o; o.x = cvt_pk_bf16(v0[0], v0[1]); o.y = cvt_pk_bf16(v0[2], v0[3]); o.z = cvt_pk_bf16(v1[0], v1[1]); o.w = cvt_pk_bf16(v1[2], v1[3]);
;                               *(u32x4*)(outb + ro + bj * HALF) = o; }
;                     else { __builtin_nontemporal_store(v0, (f32x4*)(outf + ro + bj * HALF)); __builtin_nontemporal_store(v1, (f32x4*)(outf + ro + bj * HALF + 4)); }
.LBB0_676:
	s_waitcnt vmcnt(0)
	s_nop 0
	v_lshlrev_b32_e32 v8, 16, v64
	v_and_b32_e32 v9, 0xffff0000, v64
	v_lshlrev_b32_e32 v10, 16, v65
	v_and_b32_e32 v11, 0xffff0000, v65
	v_lshlrev_b32_e32 v12, 16, v66
	v_and_b32_e32 v13, 0xffff0000, v66
	v_lshlrev_b32_e32 v14, 16, v67
	v_and_b32_e32 v15, 0xffff0000, v67
	v_pk_fma_f32 v[6:7], v[6:7], v[74:75], v[10:11]
	v_pk_fma_f32 v[4:5], v[4:5], v[72:73], v[8:9]
	v_pk_fma_f32 v[2:3], v[2:3], v[70:71], v[14:15]
	v_pk_fma_f32 v[0:1], v[0:1], v[68:69], v[12:13]
	s_mov_b64 s[34:35], -1
	s_and_b64 vcc, exec, s[8:9]
	s_cbranch_vccz .LBB0_679
	v_cvt_pk_bf16_f32 v8, v4, v5
	v_cvt_pk_bf16_f32 v9, v6, v7
	v_cvt_pk_bf16_f32 v10, v0, v1
	v_cvt_pk_bf16_f32 v11, v2, v3
	global_store_dwordx4 v[16:17], v[8:11], off offset:256 sc1
	s_cbranch_execz .LBB0_680
